# v16 plus per-row pos loads hoisted out of the P2 q/k RoPE epilogue ladder
# baseline (speedup 1.0000x reference)
;     __device__ __forceinline__ void operator()(const f32x4 (&acc)[2][2][4][2], const Unit& u, int wr, int wc, int fr, int fq) const {
;     ...
;         if (u.pn < 16) {
;             const bool isk = u.pn >= 8; const int head = u.pn & 7;
;             bf16_t* base = (isk ? K : Q) + head * 256 + cl;
;             f32x4 invf[2];
; #pragma unroll
;             for (int bj = 0; bj < 2; ++bj) invf[bj] = *(const f32x4*)(INVF256 + 64 * bj + 16 * wc + 4 * fq);
;             const float lg = __log2f(1.0f - exp2f(-5.0f - (float)head));
; #pragma unroll
;             for (int ai = 0; ai < 2; ++ai)
; #pragma unroll
;                 for (int m = 0; m < 4; ++m) {
;                     const int row = row0 + ai * HALF + m * 16; const float p = (float)pos[row];
;                     const float jj = (float)(wr * 64 + m * 16 + fr + 1);
;                     const float dec = isk ? 0.0625f * exp2f(-lg * jj) : exp2f(lg * jj);
.LBB0_336:
	v_ashrrev_i32_e32 v159, 31, v158
	v_lshl_add_u64 v[160:161], v[158:159], 2, s[44:45]
	global_load_dwordx4 v[132:135], v[148:149], off
	global_load_dwordx4 v[128:131], v[148:149], off offset:256
	global_load_dword v144, v[160:161], off
	global_load_dword v240, v[160:161], off offset:64
	global_load_dword v241, v[160:161], off offset:128
	global_load_dword v242, v[160:161], off offset:192
	global_load_dword v243, v[160:161], off offset:512
	global_load_dword v244, v[160:161], off offset:576
	global_load_dword v245, v[160:161], off offset:640
	global_load_dword v246, v[160:161], off offset:704
	s_cmp_gt_i32 s0, 7
	s_cselect_b64 s[4:5], -1, 0
	s_cmp_lt_i32 s0, 8
	s_cselect_b64 s[36:37], -1, 0
	s_and_b32 s31, s0, 7
	v_cvt_f32_ubyte0_e32 v162, s31
	v_sub_f32_e32 v162, 0xc0a00000, v162
	v_cmp_gt_f32_e32 vcc, s68, v162
	s_and_b64 s[0:1], vcc, exec
	s_cselect_b32 s0, 0xffffffc0, 0
	v_cndmask_b32_e32 v163, 0, v173, vcc
	v_add_f32_e32 v162, v162, v163
	v_exp_f32_e32 v162, v162
	s_mov_b64 s[48:49], -1
	s_and_b64 vcc, exec, s[36:37]
	v_ldexp_f32 v162, v162, s0
	v_sub_f32_e32 v162, 1.0, v162
	v_log_f32_e32 v175, v162
	s_nop 0
	v_mul_f32_e32 v176, v175, v165
	v_cmp_gt_f32_e64 s[0:1], s68, v176
	s_cbranch_vccz .LBB0_338
	s_nop 0
	v_cndmask_b32_e64 v162, 0, v173, s[0:1]
	v_fmac_f32_e32 v162, v175, v165
	v_exp_f32_e32 v162, v162
	v_cndmask_b32_e64 v163, 0, v174, s[0:1]
	s_mov_b64 s[48:49], 0
	v_ldexp_f32 v178, v162, v163

;     __device__ __forceinline__ void operator()(const f32x4 (&acc)[2][2][4][2], const Unit& u, int wr, int wc, int fr, int fq) const {
;     ...
;                 for (int m = 0; m < 4; ++m) {
;                     const int row = row0 + ai * HALF + m * 16; const float p = (float)pos[row];
;                     const float jj = (float)(wr * 64 + m * 16 + fr + 1);
;                     const float dec = isk ? 0.0625f * exp2f(-lg * jj) : exp2f(lg * jj);
; #pragma unroll
;                     for (int bj = 0; bj < 2; ++bj) { f32x4 o0, o1;
; #pragma unroll
;                         for (int e = 0; e < 4; ++e) { float s, c; sincos_rr(p * invf[bj][e], s, c);
;                             const float x1 = acc[ai][bj][m][0][e], x2 = acc[ai][bj][m][1][e];
;                             o0[e] = (x1 * c - x2 * s) * dec; o1[e] = (x2 * c + x1 * s) * dec; }
;                         st8(base + (size_t)row * 2048 + bj * HALF, o0, o1); }
.LBB0_340:
	s_and_b64 s[0:1], s[4:5], exec
	s_cselect_b32 s0, s69, 0xe000000
	s_add_u32 s0, s90, s0
	s_waitcnt vmcnt(0)
	v_cvt_f32_i32_e32 v179, v144
	s_addc_u32 s1, s91, 0
	s_lshl_b32 s4, s31, 9
	s_add_u32 s0, s0, s4
	s_addc_u32 s1, s1, 0
	v_lshlrev_b32_e32 v144, 1, v146
	v_lshl_add_u64 v[162:163], s[0:1], 0, v[144:145]
	v_mul_f32_e32 v144, v132, v179
	v_mul_f32_e32 v182, 0.15915494, v144
	v_rndne_f32_e32 v182, v182
	v_fmac_f32_e32 v144, 0xc0c90fdb, v182
	v_fmac_f32_e32 v144, 0x343bbd2e, v182
	v_mul_f32_e32 v144, 0.15915494, v144
	v_sin_f32_e32 v183, v144
	v_cos_f32_e32 v182, v144
	v_mov_b32_e32 v184, v124
	v_mov_b32_e32 v185, v120
	v_lshlrev_b64 v[180:181], 12, v[158:159]
	v_pk_mul_f32 v[186:187], v[184:185], v[182:183]
	v_lshl_add_u64 v[180:181], v[162:163], 0, v[180:181]
	v_sub_f32_e32 v120, v186, v187
	v_mul_f32_e32 v144, v120, v178
	v_mul_f32_e32 v120, v133, v179
	v_mul_f32_e32 v124, 0.15915494, v120
	v_rndne_f32_e32 v124, v124
	v_fmac_f32_e32 v120, 0xc0c90fdb, v124
	v_fmac_f32_e32 v120, 0x343bbd2e, v124
	v_mov_b32_e32 v186, v183
	v_mov_b32_e32 v187, v182
	v_mul_f32_e32 v120, 0.15915494, v120
	v_pk_mul_f32 v[182:183], v[184:185], v[186:187]
	v_sin_f32_e32 v185, v120
	v_cos_f32_e32 v184, v120
	v_add_f32_e32 v120, v182, v183
	v_mul_f32_e32 v186, v120, v178
	v_mov_b32_e32 v120, v125
	v_pk_mul_f32 v[124:125], v[120:121], v[184:185]
	s_mov_b64 s[48:49], -1
	v_sub_f32_e32 v124, v124, v125
	v_mul_f32_e32 v187, v124, v178
	v_mov_b32_e32 v124, v185
	v_mov_b32_e32 v125, v184
	v_pk_mul_f32 v[120:121], v[120:121], v[124:125]
	v_mov_b32_e32 v125, v122
	v_add_f32_e32 v124, v120, v121
	v_mul_f32_e32 v120, v134, v179
	v_mul_f32_e32 v121, 0.15915494, v120
	v_rndne_f32_e32 v121, v121
	v_fmac_f32_e32 v120, 0xc0c90fdb, v121
	v_fmac_f32_e32 v120, 0x343bbd2e, v121
	v_mul_f32_e32 v120, 0.15915494, v120
	v_sin_f32_e32 v121, v120
	v_cos_f32_e32 v120, v120
	v_mul_f32_e32 v184, v124, v178
	v_mov_b32_e32 v124, v126
	s_andn2_b64 vcc, exec, s[36:37]
	v_pk_mul_f32 v[182:183], v[124:125], v[120:121]
	s_nop 0
	v_sub_f32_e32 v122, v182, v183
	v_mul_f32_e32 v126, v122, v178
	v_mov_b32_e32 v182, v121
	v_mov_b32_e32 v183, v120
	v_mul_f32_e32 v122, v135, v179
	v_pk_mul_f32 v[120:121], v[124:125], v[182:183]
	v_mul_f32_e32 v124, 0.15915494, v122
	v_rndne_f32_e32 v124, v124
	v_fmac_f32_e32 v122, 0xc0c90fdb, v124
	v_fmac_f32_e32 v122, 0x343bbd2e, v124
	v_mul_f32_e32 v122, 0.15915494, v122
	v_sin_f32_e32 v125, v122
	v_cos_f32_e32 v124, v122
	v_add_f32_e32 v120, v120, v121
	v_mov_b32_e32 v122, v127
	v_mul_f32_e32 v182, v120, v178
	v_pk_mul_f32 v[120:121], v[122:123], v[124:125]
	s_nop 0
	v_sub_f32_e32 v120, v120, v121
	v_mov_b32_e32 v121, v124
	v_mul_f32_e32 v124, v128, v179
	v_mul_f32_e32 v127, v120, v178
	v_mov_b32_e32 v120, v125
	v_mul_f32_e32 v125, 0.15915494, v124
	v_rndne_f32_e32 v125, v125
	v_fmac_f32_e32 v124, 0xc0c90fdb, v125
	v_fmac_f32_e32 v124, 0x343bbd2e, v125
	v_mul_f32_e32 v124, 0.15915494, v124
	v_pk_mul_f32 v[120:121], v[122:123], v[120:121]
	v_sin_f32_e32 v125, v124
	v_cos_f32_e32 v124, v124
	v_add_f32_e32 v120, v120, v121
	v_mul_f32_e32 v123, v120, v178
	v_cvt_pk_bf16_f32 v120, v144, v187
	v_cvt_pk_bf16_f32 v121, v126, v127
	v_cvt_pk_bf16_f32 v122, v186, v184
	v_cvt_pk_bf16_f32 v123, v182, v123
	global_store_dwordx4 v[180:181], v[120:123], off
	s_nop 1
	v_mov_b32_e32 v120, v116
	v_mov_b32_e32 v121, v112
	v_pk_mul_f32 v[122:123], v[120:121], v[124:125]
	s_nop 0
	v_sub_f32_e32 v112, v122, v123
	v_mul_f32_e32 v126, v112, v178
	v_mul_f32_e32 v112, v129, v179
	v_mul_f32_e32 v116, 0.15915494, v112
	v_rndne_f32_e32 v116, v116
	v_fmac_f32_e32 v112, 0xc0c90fdb, v116
	v_fmac_f32_e32 v112, 0x343bbd2e, v116
	v_mov_b32_e32 v122, v125
	v_mov_b32_e32 v123, v124
	v_mul_f32_e32 v112, 0.15915494, v112
	v_pk_mul_f32 v[120:121], v[120:121], v[122:123]
	v_sin_f32_e32 v123, v112
	v_cos_f32_e32 v122, v112
	v_add_f32_e32 v112, v120, v121
	v_mul_f32_e32 v124, v112, v178
	v_mov_b32_e32 v112, v117
	v_pk_mul_f32 v[116:117], v[112:113], v[122:123]
	s_nop 0
	v_sub_f32_e32 v116, v116, v117
	v_mul_f32_e32 v125, v116, v178
	v_mov_b32_e32 v116, v123
	v_mov_b32_e32 v117, v122
	v_pk_mul_f32 v[112:113], v[112:113], v[116:117]
	v_mov_b32_e32 v117, v114
	v_add_f32_e32 v116, v112, v113
	v_mul_f32_e32 v112, v130, v179
	v_mul_f32_e32 v113, 0.15915494, v112
	v_rndne_f32_e32 v113, v113
	v_fmac_f32_e32 v112, 0xc0c90fdb, v113
	v_fmac_f32_e32 v112, 0x343bbd2e, v113
	v_mul_f32_e32 v112, 0.15915494, v112
	v_sin_f32_e32 v113, v112
	v_cos_f32_e32 v112, v112
	v_mul_f32_e32 v122, v116, v178
	v_mov_b32_e32 v116, v118
	v_pk_mul_f32 v[120:121], v[116:117], v[112:113]
	s_nop 0
	v_sub_f32_e32 v114, v120, v121
	v_mul_f32_e32 v118, v114, v178
	v_mov_b32_e32 v120, v113
	v_mov_b32_e32 v121, v112
	v_mul_f32_e32 v114, v131, v179
	v_pk_mul_f32 v[112:113], v[116:117], v[120:121]
	v_mul_f32_e32 v116, 0.15915494, v114
	v_rndne_f32_e32 v116, v116
	v_fmac_f32_e32 v114, 0xc0c90fdb, v116
	v_fmac_f32_e32 v114, 0x343bbd2e, v116
	v_mul_f32_e32 v114, 0.15915494, v114
	v_sin_f32_e32 v117, v114
	v_cos_f32_e32 v116, v114
	v_add_f32_e32 v112, v112, v113
	v_mov_b32_e32 v114, v119
	v_mul_f32_e32 v120, v112, v178
	v_pk_mul_f32 v[112:113], v[114:115], v[116:117]
	s_nop 0
	v_sub_f32_e32 v112, v112, v113
	v_mul_f32_e32 v119, v112, v178
	v_mov_b32_e32 v112, v117
	v_mov_b32_e32 v113, v116
	v_pk_mul_f32 v[112:113], v[114:115], v[112:113]
	s_nop 0
	v_add_f32_e32 v112, v112, v113
	v_mul_f32_e32 v115, v112, v178
	v_cvt_pk_bf16_f32 v112, v126, v125
	v_cvt_pk_bf16_f32 v113, v118, v119
	v_cvt_pk_bf16_f32 v114, v124, v122
	v_cvt_pk_bf16_f32 v115, v120, v115
	global_store_dwordx4 v[180:181], v[112:115], off offset:256
	s_nop 1
	v_mov_b32_e32 v115, v240
	s_nop 0
	v_cndmask_b32_e64 v112, 0, 1, s[36:37]
	v_cmp_ne_u32_e64 s[4:5], 1, v112
	v_mul_f32_e32 v112, v175, v166
	v_cmp_gt_f32_e64 s[0:1], s68, v112
	s_cbranch_vccnz .LBB0_342
	s_nop 0
	v_cndmask_b32_e64 v113, 0, v173, s[0:1]
	v_fmac_f32_e32 v113, v175, v166
	v_exp_f32_e32 v113, v113
	v_cndmask_b32_e64 v114, 0, v174, s[0:1]
	s_mov_b64 s[48:49], 0
	v_ldexp_f32 v114, v113, v114

;     __device__ __forceinline__ void operator()(const f32x4 (&acc)[2][2][4][2], const Unit& u, int wr, int wc, int fr, int fq) const {
;     ...
;                 for (int m = 0; m < 4; ++m) {
;                     const int row = row0 + ai * HALF + m * 16; const float p = (float)pos[row];
;                     const float jj = (float)(wr * 64 + m * 16 + fr + 1);
;                     const float dec = isk ? 0.0625f * exp2f(-lg * jj) : exp2f(lg * jj);
; #pragma unroll
;                     for (int bj = 0; bj < 2; ++bj) { f32x4 o0, o1;
; #pragma unroll
;                         for (int e = 0; e < 4; ++e) { float s, c; sincos_rr(p * invf[bj][e], s, c);
;                             const float x1 = acc[ai][bj][m][0][e], x2 = acc[ai][bj][m][1][e];
;                             o0[e] = (x1 * c - x2 * s) * dec; o1[e] = (x2 * c + x1 * s) * dec; }
;                         st8(base + (size_t)row * 2048 + bj * HALF, o0, o1); }
.LBB0_344:
	v_cvt_f32_i32_e32 v115, v115
	v_mov_b32_e32 v120, v108
	v_mov_b32_e32 v121, v104
	v_or_b32_e32 v116, 16, v158
	v_mul_f32_e32 v118, v132, v115
	v_mul_f32_e32 v119, 0.15915494, v118
	v_rndne_f32_e32 v119, v119
	v_fmac_f32_e32 v118, 0xc0c90fdb, v119
	v_fmac_f32_e32 v118, 0x343bbd2e, v119
	v_mul_f32_e32 v118, 0.15915494, v118
	v_sin_f32_e32 v119, v118
	v_cos_f32_e32 v118, v118
	v_ashrrev_i32_e32 v117, 31, v116
	v_lshlrev_b64 v[116:117], 12, v[116:117]
	v_lshl_add_u64 v[116:117], v[162:163], 0, v[116:117]
	v_pk_mul_f32 v[122:123], v[120:121], v[118:119]
	s_mov_b64 s[36:37], -1
	v_sub_f32_e32 v104, v122, v123
	v_mul_f32_e32 v124, v104, v114
	v_mul_f32_e32 v104, v133, v115
	v_mul_f32_e32 v108, 0.15915494, v104
	v_rndne_f32_e32 v108, v108
	v_fmac_f32_e32 v104, 0xc0c90fdb, v108
	v_fmac_f32_e32 v104, 0x343bbd2e, v108
	v_mov_b32_e32 v122, v119
	v_mov_b32_e32 v123, v118
	v_mul_f32_e32 v104, 0.15915494, v104
	v_pk_mul_f32 v[118:119], v[120:121], v[122:123]
	v_sin_f32_e32 v121, v104
	v_cos_f32_e32 v120, v104
	v_add_f32_e32 v104, v118, v119
	v_mul_f32_e32 v122, v104, v114
	v_mov_b32_e32 v104, v109
	v_pk_mul_f32 v[108:109], v[104:105], v[120:121]
	s_and_b64 vcc, exec, s[4:5]
	v_sub_f32_e32 v108, v108, v109
	v_mul_f32_e32 v123, v108, v114
	v_mov_b32_e32 v108, v121
	v_mov_b32_e32 v109, v120
	v_pk_mul_f32 v[104:105], v[104:105], v[108:109]
	v_mov_b32_e32 v109, v106
	v_add_f32_e32 v108, v104, v105
	v_mul_f32_e32 v104, v134, v115
	v_mul_f32_e32 v105, 0.15915494, v104
	v_rndne_f32_e32 v105, v105
	v_fmac_f32_e32 v104, 0xc0c90fdb, v105
	v_fmac_f32_e32 v104, 0x343bbd2e, v105
	v_mul_f32_e32 v104, 0.15915494, v104
	v_sin_f32_e32 v105, v104
	v_cos_f32_e32 v104, v104
	v_mul_f32_e32 v120, v108, v114
	v_mov_b32_e32 v108, v110
	v_pk_mul_f32 v[118:119], v[108:109], v[104:105]
	s_nop 0
	v_sub_f32_e32 v106, v118, v119
	v_mul_f32_e32 v110, v106, v114
	v_mov_b32_e32 v118, v105
	v_mov_b32_e32 v119, v104
	v_mul_f32_e32 v106, v135, v115
	v_pk_mul_f32 v[104:105], v[108:109], v[118:119]
	v_mul_f32_e32 v108, 0.15915494, v106
	v_rndne_f32_e32 v108, v108
	v_fmac_f32_e32 v106, 0xc0c90fdb, v108
	v_fmac_f32_e32 v106, 0x343bbd2e, v108
	v_mul_f32_e32 v106, 0.15915494, v106
	v_sin_f32_e32 v109, v106
	v_cos_f32_e32 v108, v106
	v_add_f32_e32 v104, v104, v105
	v_mov_b32_e32 v106, v111
	v_mul_f32_e32 v118, v104, v114
	v_pk_mul_f32 v[104:105], v[106:107], v[108:109]
	s_nop 0
	v_sub_f32_e32 v104, v104, v105
	v_mov_b32_e32 v105, v108
	v_mul_f32_e32 v108, v128, v115
	v_mul_f32_e32 v111, v104, v114
	v_mov_b32_e32 v104, v109
	v_mul_f32_e32 v109, 0.15915494, v108
	v_rndne_f32_e32 v109, v109
	v_fmac_f32_e32 v108, 0xc0c90fdb, v109
	v_fmac_f32_e32 v108, 0x343bbd2e, v109
	v_mul_f32_e32 v108, 0.15915494, v108
	v_pk_mul_f32 v[104:105], v[106:107], v[104:105]
	v_sin_f32_e32 v109, v108
	v_cos_f32_e32 v108, v108
	v_add_f32_e32 v104, v104, v105
	v_mul_f32_e32 v107, v104, v114
	v_cvt_pk_bf16_f32 v104, v124, v123
	v_cvt_pk_bf16_f32 v105, v110, v111
	v_cvt_pk_bf16_f32 v106, v122, v120
	v_cvt_pk_bf16_f32 v107, v118, v107
	global_store_dwordx4 v[116:117], v[104:107], off
	s_nop 1
	v_mov_b32_e32 v104, v100
	v_mov_b32_e32 v105, v96
	v_pk_mul_f32 v[106:107], v[104:105], v[108:109]
	s_nop 0
	v_sub_f32_e32 v96, v106, v107
	v_mul_f32_e32 v110, v96, v114
	v_mul_f32_e32 v96, v129, v115
	v_mul_f32_e32 v100, 0.15915494, v96
	v_rndne_f32_e32 v100, v100
	v_fmac_f32_e32 v96, 0xc0c90fdb, v100
	v_fmac_f32_e32 v96, 0x343bbd2e, v100
	v_mov_b32_e32 v106, v109
	v_mov_b32_e32 v107, v108
	v_mul_f32_e32 v96, 0.15915494, v96
	v_pk_mul_f32 v[104:105], v[104:105], v[106:107]
	v_sin_f32_e32 v107, v96
	v_cos_f32_e32 v106, v96
	v_add_f32_e32 v96, v104, v105
	v_mul_f32_e32 v108, v96, v114
	v_mov_b32_e32 v96, v101
	v_pk_mul_f32 v[100:101], v[96:97], v[106:107]
	s_nop 0
	v_sub_f32_e32 v100, v100, v101
	v_mul_f32_e32 v109, v100, v114
	v_mov_b32_e32 v100, v107
	v_mov_b32_e32 v101, v106
	v_pk_mul_f32 v[96:97], v[96:97], v[100:101]
	v_mov_b32_e32 v101, v98
	v_add_f32_e32 v100, v96, v97
	v_mul_f32_e32 v96, v130, v115
	v_mul_f32_e32 v97, 0.15915494, v96
	v_rndne_f32_e32 v97, v97
	v_fmac_f32_e32 v96, 0xc0c90fdb, v97
	v_fmac_f32_e32 v96, 0x343bbd2e, v97
	v_mul_f32_e32 v96, 0.15915494, v96
	v_sin_f32_e32 v97, v96
	v_cos_f32_e32 v96, v96
	v_mul_f32_e32 v106, v100, v114
	v_mov_b32_e32 v100, v102
	v_pk_mul_f32 v[104:105], v[100:101], v[96:97]
	s_nop 0
	v_sub_f32_e32 v98, v104, v105
	v_mul_f32_e32 v102, v98, v114
	v_mov_b32_e32 v104, v97
	v_mov_b32_e32 v105, v96
	v_mul_f32_e32 v98, v131, v115
	v_pk_mul_f32 v[96:97], v[100:101], v[104:105]
	v_mul_f32_e32 v100, 0.15915494, v98
	v_rndne_f32_e32 v100, v100
	v_fmac_f32_e32 v98, 0xc0c90fdb, v100
	v_fmac_f32_e32 v98, 0x343bbd2e, v100
	v_mul_f32_e32 v98, 0.15915494, v98
	v_sin_f32_e32 v101, v98
	v_cos_f32_e32 v100, v98
	v_add_f32_e32 v96, v96, v97
	v_mov_b32_e32 v98, v103
	v_mul_f32_e32 v104, v96, v114
	v_pk_mul_f32 v[96:97], v[98:99], v[100:101]
	s_nop 0
	v_sub_f32_e32 v96, v96, v97
	v_mul_f32_e32 v103, v96, v114
	v_mov_b32_e32 v96, v101
	v_mov_b32_e32 v97, v100
	v_pk_mul_f32 v[96:97], v[98:99], v[96:97]
	s_nop 0
	v_add_f32_e32 v96, v96, v97
	v_mul_f32_e32 v99, v96, v114
	v_cvt_pk_bf16_f32 v96, v110, v109
	v_cvt_pk_bf16_f32 v97, v102, v103
	v_cvt_pk_bf16_f32 v98, v108, v106
	v_cvt_pk_bf16_f32 v99, v104, v99
	global_store_dwordx4 v[116:117], v[96:99], off offset:256
	s_nop 1
	v_mov_b32_e32 v99, v241
	s_nop 0
	v_mul_f32_e32 v96, v175, v167
	v_cmp_gt_f32_e64 s[0:1], s68, v96
	s_cbranch_vccnz .LBB0_346
	s_nop 0
	v_cndmask_b32_e64 v97, 0, v173, s[0:1]
	v_fmac_f32_e32 v97, v175, v167
	v_exp_f32_e32 v97, v97
	v_cndmask_b32_e64 v98, 0, v174, s[0:1]
	s_mov_b64 s[36:37], 0
	v_ldexp_f32 v98, v97, v98

;     __device__ __forceinline__ void operator()(const f32x4 (&acc)[2][2][4][2], const Unit& u, int wr, int wc, int fr, int fq) const {
;     ...
;                 for (int m = 0; m < 4; ++m) {
;                     const int row = row0 + ai * HALF + m * 16; const float p = (float)pos[row];
;                     const float jj = (float)(wr * 64 + m * 16 + fr + 1);
;                     const float dec = isk ? 0.0625f * exp2f(-lg * jj) : exp2f(lg * jj);
; #pragma unroll
;                     for (int bj = 0; bj < 2; ++bj) { f32x4 o0, o1;
; #pragma unroll
;                         for (int e = 0; e < 4; ++e) { float s, c; sincos_rr(p * invf[bj][e], s, c);
;                             const float x1 = acc[ai][bj][m][0][e], x2 = acc[ai][bj][m][1][e];
;                             o0[e] = (x1 * c - x2 * s) * dec; o1[e] = (x2 * c + x1 * s) * dec; }
;                         st8(base + (size_t)row * 2048 + bj * HALF, o0, o1); }
.LBB0_348:
	v_cvt_f32_i32_e32 v99, v99
	v_mov_b32_e32 v104, v92
	v_mov_b32_e32 v105, v88
	v_or_b32_e32 v100, 32, v158
	v_mul_f32_e32 v102, v132, v99
	v_mul_f32_e32 v103, 0.15915494, v102
	v_rndne_f32_e32 v103, v103
	v_fmac_f32_e32 v102, 0xc0c90fdb, v103
	v_fmac_f32_e32 v102, 0x343bbd2e, v103
	v_mul_f32_e32 v102, 0.15915494, v102
	v_sin_f32_e32 v103, v102
	v_cos_f32_e32 v102, v102
	v_ashrrev_i32_e32 v101, 31, v100
	v_lshlrev_b64 v[100:101], 12, v[100:101]
	v_lshl_add_u64 v[100:101], v[162:163], 0, v[100:101]
	v_pk_mul_f32 v[106:107], v[104:105], v[102:103]
	s_mov_b64 s[36:37], -1
	v_sub_f32_e32 v88, v106, v107
	v_mul_f32_e32 v108, v88, v98
	v_mul_f32_e32 v88, v133, v99
	v_mul_f32_e32 v92, 0.15915494, v88
	v_rndne_f32_e32 v92, v92
	v_fmac_f32_e32 v88, 0xc0c90fdb, v92
	v_fmac_f32_e32 v88, 0x343bbd2e, v92
	v_mov_b32_e32 v106, v103
	v_mov_b32_e32 v107, v102
	v_mul_f32_e32 v88, 0.15915494, v88
	v_pk_mul_f32 v[102:103], v[104:105], v[106:107]
	v_sin_f32_e32 v105, v88
	v_cos_f32_e32 v104, v88
	v_add_f32_e32 v88, v102, v103
	v_mul_f32_e32 v106, v88, v98
	v_mov_b32_e32 v88, v93
	v_pk_mul_f32 v[92:93], v[88:89], v[104:105]
	s_and_b64 vcc, exec, s[4:5]
	v_sub_f32_e32 v92, v92, v93
	v_mul_f32_e32 v107, v92, v98
	v_mov_b32_e32 v92, v105
	v_mov_b32_e32 v93, v104
	v_pk_mul_f32 v[88:89], v[88:89], v[92:93]
	v_mov_b32_e32 v93, v90
	v_add_f32_e32 v92, v88, v89
	v_mul_f32_e32 v88, v134, v99
	v_mul_f32_e32 v89, 0.15915494, v88
	v_rndne_f32_e32 v89, v89
	v_fmac_f32_e32 v88, 0xc0c90fdb, v89
	v_fmac_f32_e32 v88, 0x343bbd2e, v89
	v_mul_f32_e32 v88, 0.15915494, v88
	v_sin_f32_e32 v89, v88
	v_cos_f32_e32 v88, v88
	v_mul_f32_e32 v104, v92, v98
	v_mov_b32_e32 v92, v94
	v_pk_mul_f32 v[102:103], v[92:93], v[88:89]
	s_nop 0
	v_sub_f32_e32 v90, v102, v103
	v_mul_f32_e32 v94, v90, v98
	v_mov_b32_e32 v102, v89
	v_mov_b32_e32 v103, v88
	v_mul_f32_e32 v90, v135, v99
	v_pk_mul_f32 v[88:89], v[92:93], v[102:103]
	v_mul_f32_e32 v92, 0.15915494, v90
	v_rndne_f32_e32 v92, v92
	v_fmac_f32_e32 v90, 0xc0c90fdb, v92
	v_fmac_f32_e32 v90, 0x343bbd2e, v92
	v_mul_f32_e32 v90, 0.15915494, v90
	v_sin_f32_e32 v93, v90
	v_cos_f32_e32 v92, v90
	v_add_f32_e32 v88, v88, v89
	v_mov_b32_e32 v90, v95
	v_mul_f32_e32 v102, v88, v98
	v_pk_mul_f32 v[88:89], v[90:91], v[92:93]
	s_nop 0
	v_sub_f32_e32 v88, v88, v89
	v_mov_b32_e32 v89, v92
	v_mul_f32_e32 v92, v128, v99
	v_mul_f32_e32 v95, v88, v98
	v_mov_b32_e32 v88, v93
	v_mul_f32_e32 v93, 0.15915494, v92
	v_rndne_f32_e32 v93, v93
	v_fmac_f32_e32 v92, 0xc0c90fdb, v93
	v_fmac_f32_e32 v92, 0x343bbd2e, v93
	v_mul_f32_e32 v92, 0.15915494, v92
	v_pk_mul_f32 v[88:89], v[90:91], v[88:89]
	v_sin_f32_e32 v93, v92
	v_cos_f32_e32 v92, v92
	v_add_f32_e32 v88, v88, v89
	v_mul_f32_e32 v91, v88, v98
	v_cvt_pk_bf16_f32 v88, v108, v107
	v_cvt_pk_bf16_f32 v89, v94, v95
	v_cvt_pk_bf16_f32 v90, v106, v104
	v_cvt_pk_bf16_f32 v91, v102, v91
	global_store_dwordx4 v[100:101], v[88:91], off
	s_nop 1
	v_mov_b32_e32 v88, v84
	v_mov_b32_e32 v89, v80
	v_pk_mul_f32 v[90:91], v[88:89], v[92:93]
	s_nop 0
	v_sub_f32_e32 v80, v90, v91
	v_mul_f32_e32 v94, v80, v98
	v_mul_f32_e32 v80, v129, v99
	v_mul_f32_e32 v84, 0.15915494, v80
	v_rndne_f32_e32 v84, v84
	v_fmac_f32_e32 v80, 0xc0c90fdb, v84
	v_fmac_f32_e32 v80, 0x343bbd2e, v84
	v_mov_b32_e32 v90, v93
	v_mov_b32_e32 v91, v92
	v_mul_f32_e32 v80, 0.15915494, v80
	v_pk_mul_f32 v[88:89], v[88:89], v[90:91]
	v_sin_f32_e32 v91, v80
	v_cos_f32_e32 v90, v80
	v_add_f32_e32 v80, v88, v89
	v_mul_f32_e32 v92, v80, v98
	v_mov_b32_e32 v80, v85
	v_pk_mul_f32 v[84:85], v[80:81], v[90:91]
	s_nop 0
	v_sub_f32_e32 v84, v84, v85
	v_mul_f32_e32 v93, v84, v98
	v_mov_b32_e32 v84, v91
	v_mov_b32_e32 v85, v90
	v_pk_mul_f32 v[80:81], v[80:81], v[84:85]
	v_mov_b32_e32 v85, v82
	v_add_f32_e32 v84, v80, v81
	v_mul_f32_e32 v80, v130, v99
	v_mul_f32_e32 v81, 0.15915494, v80
	v_rndne_f32_e32 v81, v81
	v_fmac_f32_e32 v80, 0xc0c90fdb, v81
	v_fmac_f32_e32 v80, 0x343bbd2e, v81
	v_mul_f32_e32 v80, 0.15915494, v80
	v_sin_f32_e32 v81, v80
	v_cos_f32_e32 v80, v80
	v_mul_f32_e32 v90, v84, v98
	v_mov_b32_e32 v84, v86
	v_pk_mul_f32 v[88:89], v[84:85], v[80:81]
	s_nop 0
	v_sub_f32_e32 v82, v88, v89
	v_mul_f32_e32 v86, v82, v98
	v_mov_b32_e32 v88, v81
	v_mov_b32_e32 v89, v80
	v_mul_f32_e32 v82, v131, v99
	v_pk_mul_f32 v[80:81], v[84:85], v[88:89]
	v_mul_f32_e32 v84, 0.15915494, v82
	v_rndne_f32_e32 v84, v84
	v_fmac_f32_e32 v82, 0xc0c90fdb, v84
	v_fmac_f32_e32 v82, 0x343bbd2e, v84
	v_mul_f32_e32 v82, 0.15915494, v82
	v_sin_f32_e32 v85, v82
	v_cos_f32_e32 v84, v82
	v_add_f32_e32 v80, v80, v81
	v_mov_b32_e32 v82, v87
	v_mul_f32_e32 v88, v80, v98
	v_pk_mul_f32 v[80:81], v[82:83], v[84:85]
	s_nop 0
	v_sub_f32_e32 v80, v80, v81
	v_mul_f32_e32 v87, v80, v98
	v_mov_b32_e32 v80, v85
	v_mov_b32_e32 v81, v84
	v_pk_mul_f32 v[80:81], v[82:83], v[80:81]
	s_nop 0
	v_add_f32_e32 v80, v80, v81
	v_mul_f32_e32 v83, v80, v98
	v_cvt_pk_bf16_f32 v80, v94, v93
	v_cvt_pk_bf16_f32 v81, v86, v87
	v_cvt_pk_bf16_f32 v82, v92, v90
	v_cvt_pk_bf16_f32 v83, v88, v83
	global_store_dwordx4 v[100:101], v[80:83], off offset:256
	s_nop 1
	v_mov_b32_e32 v83, v242
	s_nop 0
	v_mul_f32_e32 v80, v175, v169
	v_cmp_gt_f32_e64 s[0:1], s68, v80
	s_cbranch_vccnz .LBB0_350
	s_nop 0
	v_cndmask_b32_e64 v81, 0, v173, s[0:1]
	v_fmac_f32_e32 v81, v175, v169
	v_exp_f32_e32 v81, v81
	v_cndmask_b32_e64 v82, 0, v174, s[0:1]
	s_mov_b64 s[36:37], 0
	v_ldexp_f32 v82, v81, v82

;     __device__ __forceinline__ void operator()(const f32x4 (&acc)[2][2][4][2], const Unit& u, int wr, int wc, int fr, int fq) const {
;     ...
;                 for (int m = 0; m < 4; ++m) {
;                     const int row = row0 + ai * HALF + m * 16; const float p = (float)pos[row];
;                     const float jj = (float)(wr * 64 + m * 16 + fr + 1);
;                     const float dec = isk ? 0.0625f * exp2f(-lg * jj) : exp2f(lg * jj);
; #pragma unroll
;                     for (int bj = 0; bj < 2; ++bj) { f32x4 o0, o1;
; #pragma unroll
;                         for (int e = 0; e < 4; ++e) { float s, c; sincos_rr(p * invf[bj][e], s, c);
;                             const float x1 = acc[ai][bj][m][0][e], x2 = acc[ai][bj][m][1][e];
;                             o0[e] = (x1 * c - x2 * s) * dec; o1[e] = (x2 * c + x1 * s) * dec; }
;                         st8(base + (size_t)row * 2048 + bj * HALF, o0, o1); }
.LBB0_352:
	v_cvt_f32_i32_e32 v83, v83
	v_mov_b32_e32 v88, v76
	v_mov_b32_e32 v89, v72
	v_or_b32_e32 v84, 48, v158
	v_mul_f32_e32 v86, v132, v83
	v_mul_f32_e32 v87, 0.15915494, v86
	v_rndne_f32_e32 v87, v87
	v_fmac_f32_e32 v86, 0xc0c90fdb, v87
	v_fmac_f32_e32 v86, 0x343bbd2e, v87
	v_mul_f32_e32 v86, 0.15915494, v86
	v_sin_f32_e32 v87, v86
	v_cos_f32_e32 v86, v86
	v_ashrrev_i32_e32 v85, 31, v84
	v_lshlrev_b64 v[84:85], 12, v[84:85]
	v_lshl_add_u64 v[84:85], v[162:163], 0, v[84:85]
	v_pk_mul_f32 v[90:91], v[88:89], v[86:87]
	s_and_b64 vcc, exec, s[4:5]
	v_sub_f32_e32 v72, v90, v91
	v_mul_f32_e32 v92, v72, v82
	v_mul_f32_e32 v72, v133, v83
	v_mul_f32_e32 v76, 0.15915494, v72
	v_rndne_f32_e32 v76, v76
	v_fmac_f32_e32 v72, 0xc0c90fdb, v76
	v_fmac_f32_e32 v72, 0x343bbd2e, v76
	v_mov_b32_e32 v90, v87
	v_mov_b32_e32 v91, v86
	v_mul_f32_e32 v72, 0.15915494, v72
	v_pk_mul_f32 v[86:87], v[88:89], v[90:91]
	v_sin_f32_e32 v89, v72
	v_cos_f32_e32 v88, v72
	v_add_f32_e32 v72, v86, v87
	v_mul_f32_e32 v90, v72, v82
	v_mov_b32_e32 v72, v77
	v_pk_mul_f32 v[76:77], v[72:73], v[88:89]
	s_mov_b64 s[0:1], -1
	v_sub_f32_e32 v76, v76, v77
	v_mul_f32_e32 v91, v76, v82
	v_mov_b32_e32 v76, v89
	v_mov_b32_e32 v77, v88
	v_pk_mul_f32 v[72:73], v[72:73], v[76:77]
	v_mov_b32_e32 v77, v74
	v_add_f32_e32 v76, v72, v73
	v_mul_f32_e32 v72, v134, v83
	v_mul_f32_e32 v73, 0.15915494, v72
	v_rndne_f32_e32 v73, v73
	v_fmac_f32_e32 v72, 0xc0c90fdb, v73
	v_fmac_f32_e32 v72, 0x343bbd2e, v73
	v_mul_f32_e32 v72, 0.15915494, v72
	v_sin_f32_e32 v73, v72
	v_cos_f32_e32 v72, v72
	v_mul_f32_e32 v88, v76, v82
	v_mov_b32_e32 v76, v78
	v_pk_mul_f32 v[86:87], v[76:77], v[72:73]
	s_nop 0
	v_sub_f32_e32 v74, v86, v87
	v_mul_f32_e32 v78, v74, v82
	v_mov_b32_e32 v86, v73
	v_mov_b32_e32 v87, v72
	v_mul_f32_e32 v74, v135, v83
	v_pk_mul_f32 v[72:73], v[76:77], v[86:87]
	v_mul_f32_e32 v76, 0.15915494, v74
	v_rndne_f32_e32 v76, v76
	v_fmac_f32_e32 v74, 0xc0c90fdb, v76
	v_fmac_f32_e32 v74, 0x343bbd2e, v76
	v_mul_f32_e32 v74, 0.15915494, v74
	v_sin_f32_e32 v77, v74
	v_cos_f32_e32 v76, v74
	v_add_f32_e32 v72, v72, v73
	v_mov_b32_e32 v74, v79
	v_mul_f32_e32 v86, v72, v82
	v_pk_mul_f32 v[72:73], v[74:75], v[76:77]
	s_nop 0
	v_sub_f32_e32 v72, v72, v73
	v_mov_b32_e32 v73, v76
	v_mul_f32_e32 v76, v128, v83
	v_mul_f32_e32 v79, v72, v82
	v_mov_b32_e32 v72, v77
	v_mul_f32_e32 v77, 0.15915494, v76
	v_rndne_f32_e32 v77, v77
	v_fmac_f32_e32 v76, 0xc0c90fdb, v77
	v_fmac_f32_e32 v76, 0x343bbd2e, v77
	v_mul_f32_e32 v76, 0.15915494, v76
	v_pk_mul_f32 v[72:73], v[74:75], v[72:73]
	v_sin_f32_e32 v77, v76
	v_cos_f32_e32 v76, v76
	v_add_f32_e32 v72, v72, v73
	v_mul_f32_e32 v75, v72, v82
	v_cvt_pk_bf16_f32 v72, v92, v91
	v_cvt_pk_bf16_f32 v73, v78, v79
	v_cvt_pk_bf16_f32 v74, v90, v88
	v_cvt_pk_bf16_f32 v75, v86, v75
	global_store_dwordx4 v[84:85], v[72:75], off
	s_nop 1
	v_mov_b32_e32 v72, v68
	v_mov_b32_e32 v73, v64
	v_pk_mul_f32 v[74:75], v[72:73], v[76:77]
	s_nop 0
	v_sub_f32_e32 v64, v74, v75
	v_mul_f32_e32 v78, v64, v82
	v_mul_f32_e32 v64, v129, v83
	v_mul_f32_e32 v68, 0.15915494, v64
	v_rndne_f32_e32 v68, v68
	v_fmac_f32_e32 v64, 0xc0c90fdb, v68
	v_fmac_f32_e32 v64, 0x343bbd2e, v68
	v_mov_b32_e32 v74, v77
	v_mov_b32_e32 v75, v76
	v_mul_f32_e32 v64, 0.15915494, v64
	v_pk_mul_f32 v[72:73], v[72:73], v[74:75]
	v_sin_f32_e32 v75, v64
	v_cos_f32_e32 v74, v64
	v_add_f32_e32 v64, v72, v73
	v_mul_f32_e32 v76, v64, v82
	v_mov_b32_e32 v64, v69
	v_pk_mul_f32 v[68:69], v[64:65], v[74:75]
	s_nop 0
	v_sub_f32_e32 v68, v68, v69
	v_mul_f32_e32 v77, v68, v82
	v_mov_b32_e32 v68, v75
	v_mov_b32_e32 v69, v74
	v_pk_mul_f32 v[64:65], v[64:65], v[68:69]
	v_mov_b32_e32 v69, v66
	v_add_f32_e32 v68, v64, v65
	v_mul_f32_e32 v64, v130, v83
	v_mul_f32_e32 v65, 0.15915494, v64
	v_rndne_f32_e32 v65, v65
	v_fmac_f32_e32 v64, 0xc0c90fdb, v65
	v_fmac_f32_e32 v64, 0x343bbd2e, v65
	v_mul_f32_e32 v64, 0.15915494, v64
	v_sin_f32_e32 v65, v64
	v_cos_f32_e32 v64, v64
	v_mul_f32_e32 v74, v68, v82
	v_mov_b32_e32 v68, v70
	v_pk_mul_f32 v[72:73], v[68:69], v[64:65]
	s_nop 0
	v_sub_f32_e32 v66, v72, v73
	v_mul_f32_e32 v70, v66, v82
	v_mov_b32_e32 v72, v65
	v_mov_b32_e32 v73, v64
	v_mul_f32_e32 v66, v131, v83
	v_pk_mul_f32 v[64:65], v[68:69], v[72:73]
	v_mul_f32_e32 v68, 0.15915494, v66
	v_rndne_f32_e32 v68, v68
	v_fmac_f32_e32 v66, 0xc0c90fdb, v68
	v_fmac_f32_e32 v66, 0x343bbd2e, v68
	v_mul_f32_e32 v66, 0.15915494, v66
	v_sin_f32_e32 v69, v66
	v_cos_f32_e32 v68, v66
	v_add_f32_e32 v64, v64, v65
	v_mov_b32_e32 v66, v71
	v_mul_f32_e32 v72, v64, v82
	v_pk_mul_f32 v[64:65], v[66:67], v[68:69]
	s_nop 0
	v_sub_f32_e32 v64, v64, v65
	v_mul_f32_e32 v71, v64, v82
	v_mov_b32_e32 v64, v69
	v_mov_b32_e32 v65, v68
	v_pk_mul_f32 v[64:65], v[66:67], v[64:65]
	s_nop 0
	v_add_f32_e32 v64, v64, v65
	v_mul_f32_e32 v67, v64, v82
	v_cvt_pk_bf16_f32 v64, v78, v77
	v_cvt_pk_bf16_f32 v65, v70, v71
	v_cvt_pk_bf16_f32 v66, v76, v74
	v_cvt_pk_bf16_f32 v67, v72, v67
	global_store_dwordx4 v[84:85], v[64:67], off offset:256
	s_nop 1
	v_mov_b32_e32 v65, v243
	s_cbranch_vccnz .LBB0_354
	v_cmp_gt_f32_e32 vcc, s68, v176
	s_mov_b64 s[0:1], 0
	s_nop 0
	v_cndmask_b32_e32 v66, 0, v173, vcc
	v_fmac_f32_e32 v66, v175, v165
	v_exp_f32_e32 v66, v66
	v_cndmask_b32_e32 v64, 0, v174, vcc
	v_ldexp_f32 v64, v66, v64

;     __device__ __forceinline__ void operator()(const f32x4 (&acc)[2][2][4][2], const Unit& u, int wr, int wc, int fr, int fq) const {
;     ...
;                 for (int m = 0; m < 4; ++m) {
;                     const int row = row0 + ai * HALF + m * 16; const float p = (float)pos[row];
;                     const float jj = (float)(wr * 64 + m * 16 + fr + 1);
;                     const float dec = isk ? 0.0625f * exp2f(-lg * jj) : exp2f(lg * jj);
; #pragma unroll
;                     for (int bj = 0; bj < 2; ++bj) { f32x4 o0, o1;
; #pragma unroll
;                         for (int e = 0; e < 4; ++e) { float s, c; sincos_rr(p * invf[bj][e], s, c);
;                             const float x1 = acc[ai][bj][m][0][e], x2 = acc[ai][bj][m][1][e];
;                             o0[e] = (x1 * c - x2 * s) * dec; o1[e] = (x2 * c + x1 * s) * dec; }
;                         st8(base + (size_t)row * 2048 + bj * HALF, o0, o1); }
.LBB0_356:
	v_cvt_f32_i32_e32 v65, v65
	v_mov_b32_e32 v68, v60
	v_lshlrev_b64 v[66:67], 12, v[158:159]
	v_lshl_add_u64 v[66:67], v[162:163], 0, v[66:67]
	v_mul_f32_e32 v60, v132, v65
	v_mul_f32_e32 v69, 0.15915494, v60
	v_rndne_f32_e32 v69, v69
	v_fmac_f32_e32 v60, 0xc0c90fdb, v69
	v_fmac_f32_e32 v60, 0x343bbd2e, v69
	v_mul_f32_e32 v60, 0.15915494, v60
	v_sin_f32_e32 v71, v60
	v_cos_f32_e32 v70, v60
	v_mov_b32_e32 v69, v56
	v_lshl_add_u64 v[72:73], v[66:67], 0, s[8:9]
	s_mov_b64 s[0:1], -1
	v_pk_mul_f32 v[74:75], v[68:69], v[70:71]
	s_nop 0
	v_sub_f32_e32 v56, v74, v75
	v_mul_f32_e32 v76, v56, v64
	v_mul_f32_e32 v56, v133, v65
	v_mul_f32_e32 v60, 0.15915494, v56
	v_rndne_f32_e32 v60, v60
	v_fmac_f32_e32 v56, 0xc0c90fdb, v60
	v_fmac_f32_e32 v56, 0x343bbd2e, v60
	v_mul_f32_e32 v56, 0.15915494, v56
	v_mov_b32_e32 v74, v71
	v_mov_b32_e32 v75, v70
	v_sin_f32_e32 v71, v56
	v_cos_f32_e32 v70, v56
	v_pk_mul_f32 v[68:69], v[68:69], v[74:75]
	s_nop 0
	v_add_f32_e32 v56, v68, v69
	v_mul_f32_e32 v74, v56, v64
	v_mov_b32_e32 v56, v61
	v_pk_mul_f32 v[60:61], v[56:57], v[70:71]
	s_nop 0
	v_sub_f32_e32 v60, v60, v61
	v_mul_f32_e32 v75, v60, v64
	v_mov_b32_e32 v60, v71
	v_mov_b32_e32 v61, v70
	v_pk_mul_f32 v[56:57], v[56:57], v[60:61]
	v_mov_b32_e32 v61, v58
	v_add_f32_e32 v60, v56, v57
	v_mul_f32_e32 v56, v134, v65
	v_mul_f32_e32 v57, 0.15915494, v56
	v_rndne_f32_e32 v57, v57
	v_fmac_f32_e32 v56, 0xc0c90fdb, v57
	v_fmac_f32_e32 v56, 0x343bbd2e, v57
	v_mul_f32_e32 v56, 0.15915494, v56
	v_sin_f32_e32 v57, v56
	v_cos_f32_e32 v56, v56
	v_mul_f32_e32 v70, v60, v64
	v_mov_b32_e32 v60, v62
	v_pk_mul_f32 v[68:69], v[60:61], v[56:57]
	s_nop 0
	v_sub_f32_e32 v58, v68, v69
	v_mul_f32_e32 v62, v58, v64
	v_mov_b32_e32 v68, v57
	v_mov_b32_e32 v69, v56
	v_mul_f32_e32 v58, v135, v65
	v_pk_mul_f32 v[56:57], v[60:61], v[68:69]
	v_mul_f32_e32 v60, 0.15915494, v58
	v_rndne_f32_e32 v60, v60
	v_fmac_f32_e32 v58, 0xc0c90fdb, v60
	v_fmac_f32_e32 v58, 0x343bbd2e, v60
	v_mul_f32_e32 v58, 0.15915494, v58
	v_sin_f32_e32 v61, v58
	v_cos_f32_e32 v60, v58
	v_add_f32_e32 v56, v56, v57
	v_mov_b32_e32 v58, v63
	v_mul_f32_e32 v68, v56, v64
	v_pk_mul_f32 v[56:57], v[58:59], v[60:61]
	s_nop 0
	v_sub_f32_e32 v56, v56, v57
	v_mul_f32_e32 v63, v56, v64
	v_mov_b32_e32 v56, v61
	v_mov_b32_e32 v57, v60
	v_pk_mul_f32 v[56:57], v[58:59], v[56:57]
	v_add_co_u32_e32 v60, vcc, s70, v66
	v_add_f32_e32 v56, v56, v57
	v_mul_f32_e32 v59, v56, v64
	v_cvt_pk_bf16_f32 v56, v76, v75
	v_cvt_pk_bf16_f32 v57, v62, v63
	v_mul_f32_e32 v62, v128, v65
	v_mul_f32_e32 v63, 0.15915494, v62
	v_rndne_f32_e32 v63, v63
	v_fmac_f32_e32 v62, 0xc0c90fdb, v63
	v_fmac_f32_e32 v62, 0x343bbd2e, v63
	v_mul_f32_e32 v62, 0.15915494, v62
	v_sin_f32_e32 v63, v62
	v_cos_f32_e32 v62, v62
	v_addc_co_u32_e32 v61, vcc, 0, v67, vcc
	v_cvt_pk_bf16_f32 v58, v74, v70
	v_cvt_pk_bf16_f32 v59, v68, v59
	global_store_dwordx4 v[60:61], v[56:59], off
	s_and_b64 vcc, exec, s[4:5]
	s_nop 0
	v_mov_b32_e32 v56, v52
	v_mov_b32_e32 v57, v48
	v_pk_mul_f32 v[58:59], v[56:57], v[62:63]
	s_nop 0
	v_sub_f32_e32 v48, v58, v59
	v_mul_f32_e32 v60, v48, v64
	v_mul_f32_e32 v48, v129, v65
	v_mul_f32_e32 v52, 0.15915494, v48
	v_rndne_f32_e32 v52, v52
	v_fmac_f32_e32 v48, 0xc0c90fdb, v52
	v_fmac_f32_e32 v48, 0x343bbd2e, v52
	v_mov_b32_e32 v58, v63
	v_mov_b32_e32 v59, v62
	v_mul_f32_e32 v48, 0.15915494, v48
	v_pk_mul_f32 v[56:57], v[56:57], v[58:59]
	v_sin_f32_e32 v59, v48
	v_cos_f32_e32 v58, v48
	v_add_f32_e32 v48, v56, v57
	v_mul_f32_e32 v61, v48, v64
	v_mov_b32_e32 v48, v53
	v_pk_mul_f32 v[52:53], v[48:49], v[58:59]
	s_nop 0
	v_sub_f32_e32 v52, v52, v53
	v_mul_f32_e32 v62, v52, v64
	v_mov_b32_e32 v52, v59
	v_mov_b32_e32 v53, v58
	v_pk_mul_f32 v[48:49], v[48:49], v[52:53]
	v_mov_b32_e32 v53, v50
	v_add_f32_e32 v52, v48, v49
	v_mul_f32_e32 v48, v130, v65
	v_mul_f32_e32 v49, 0.15915494, v48
	v_rndne_f32_e32 v49, v49
	v_fmac_f32_e32 v48, 0xc0c90fdb, v49
	v_fmac_f32_e32 v48, 0x343bbd2e, v49
	v_mul_f32_e32 v48, 0.15915494, v48
	v_sin_f32_e32 v49, v48
	v_cos_f32_e32 v48, v48
	v_mul_f32_e32 v58, v52, v64
	v_mov_b32_e32 v52, v54
	v_pk_mul_f32 v[56:57], v[52:53], v[48:49]
	s_nop 0
	v_sub_f32_e32 v50, v56, v57
	v_mul_f32_e32 v54, v50, v64
	v_mov_b32_e32 v56, v49
	v_mov_b32_e32 v57, v48
	v_mul_f32_e32 v50, v131, v65
	v_pk_mul_f32 v[48:49], v[52:53], v[56:57]
	v_mul_f32_e32 v52, 0.15915494, v50
	v_rndne_f32_e32 v52, v52
	v_fmac_f32_e32 v50, 0xc0c90fdb, v52
	v_fmac_f32_e32 v50, 0x343bbd2e, v52
	v_mul_f32_e32 v50, 0.15915494, v50
	v_sin_f32_e32 v53, v50
	v_cos_f32_e32 v52, v50
	v_add_f32_e32 v48, v48, v49
	v_mov_b32_e32 v50, v55
	v_mul_f32_e32 v56, v48, v64
	v_pk_mul_f32 v[48:49], v[50:51], v[52:53]
	s_nop 0
	v_sub_f32_e32 v48, v48, v49
	v_mul_f32_e32 v55, v48, v64
	v_mov_b32_e32 v48, v53
	v_mov_b32_e32 v49, v52
	v_pk_mul_f32 v[48:49], v[50:51], v[48:49]
	s_nop 0
	v_add_f32_e32 v48, v48, v49
	v_mul_f32_e32 v51, v48, v64
	v_cvt_pk_bf16_f32 v48, v60, v62
	v_cvt_pk_bf16_f32 v49, v54, v55
	v_cvt_pk_bf16_f32 v50, v61, v58
	v_cvt_pk_bf16_f32 v51, v56, v51
	global_store_dwordx4 v[72:73], v[48:51], off offset:256
	s_nop 1
	v_mov_b32_e32 v49, v244
	s_cbranch_vccnz .LBB0_358
	v_cmp_gt_f32_e32 vcc, s68, v112
	s_mov_b64 s[0:1], 0
	s_nop 0
	v_cndmask_b32_e32 v50, 0, v173, vcc
	v_fmac_f32_e32 v50, v175, v166
	v_exp_f32_e32 v50, v50
	v_cndmask_b32_e32 v48, 0, v174, vcc
	v_ldexp_f32 v48, v50, v48

;     __device__ __forceinline__ void operator()(const f32x4 (&acc)[2][2][4][2], const Unit& u, int wr, int wc, int fr, int fq) const {
;     ...
;                 for (int m = 0; m < 4; ++m) {
;                     const int row = row0 + ai * HALF + m * 16; const float p = (float)pos[row];
;                     const float jj = (float)(wr * 64 + m * 16 + fr + 1);
;                     const float dec = isk ? 0.0625f * exp2f(-lg * jj) : exp2f(lg * jj);
; #pragma unroll
;                     for (int bj = 0; bj < 2; ++bj) { f32x4 o0, o1;
; #pragma unroll
;                         for (int e = 0; e < 4; ++e) { float s, c; sincos_rr(p * invf[bj][e], s, c);
;                             const float x1 = acc[ai][bj][m][0][e], x2 = acc[ai][bj][m][1][e];
;                             o0[e] = (x1 * c - x2 * s) * dec; o1[e] = (x2 * c + x1 * s) * dec; }
;                         st8(base + (size_t)row * 2048 + bj * HALF, o0, o1); }
.LBB0_360:
	v_cvt_f32_i32_e32 v49, v49
	v_mov_b32_e32 v52, v44
	v_lshlrev_b64 v[50:51], 12, v[158:159]
	v_lshl_add_u64 v[50:51], v[162:163], 0, v[50:51]
	v_mul_f32_e32 v44, v132, v49
	v_mul_f32_e32 v53, 0.15915494, v44
	v_rndne_f32_e32 v53, v53
	v_fmac_f32_e32 v44, 0xc0c90fdb, v53
	v_fmac_f32_e32 v44, 0x343bbd2e, v53
	v_mul_f32_e32 v44, 0.15915494, v44
	v_sin_f32_e32 v55, v44
	v_cos_f32_e32 v54, v44
	v_mov_b32_e32 v53, v40
	v_lshl_add_u64 v[56:57], v[50:51], 0, s[24:25]
	s_mov_b64 s[0:1], -1
	v_pk_mul_f32 v[58:59], v[52:53], v[54:55]
	s_nop 0
	v_sub_f32_e32 v40, v58, v59
	v_mul_f32_e32 v60, v40, v48
	v_mul_f32_e32 v40, v133, v49
	v_mul_f32_e32 v44, 0.15915494, v40
	v_rndne_f32_e32 v44, v44
	v_fmac_f32_e32 v40, 0xc0c90fdb, v44
	v_fmac_f32_e32 v40, 0x343bbd2e, v44
	v_mul_f32_e32 v40, 0.15915494, v40
	v_mov_b32_e32 v58, v55
	v_mov_b32_e32 v59, v54
	v_sin_f32_e32 v55, v40
	v_cos_f32_e32 v54, v40
	v_pk_mul_f32 v[52:53], v[52:53], v[58:59]
	s_nop 0
	v_add_f32_e32 v40, v52, v53
	v_mul_f32_e32 v58, v40, v48
	v_mov_b32_e32 v40, v45
	v_pk_mul_f32 v[44:45], v[40:41], v[54:55]
	s_nop 0
	v_sub_f32_e32 v44, v44, v45
	v_mul_f32_e32 v59, v44, v48
	v_mov_b32_e32 v44, v55
	v_mov_b32_e32 v45, v54
	v_pk_mul_f32 v[40:41], v[40:41], v[44:45]
	v_mov_b32_e32 v45, v42
	v_add_f32_e32 v44, v40, v41
	v_mul_f32_e32 v40, v134, v49
	v_mul_f32_e32 v41, 0.15915494, v40
	v_rndne_f32_e32 v41, v41
	v_fmac_f32_e32 v40, 0xc0c90fdb, v41
	v_fmac_f32_e32 v40, 0x343bbd2e, v41
	v_mul_f32_e32 v40, 0.15915494, v40
	v_sin_f32_e32 v41, v40
	v_cos_f32_e32 v40, v40
	v_mul_f32_e32 v54, v44, v48
	v_mov_b32_e32 v44, v46
	v_pk_mul_f32 v[52:53], v[44:45], v[40:41]
	s_nop 0
	v_sub_f32_e32 v42, v52, v53
	v_mul_f32_e32 v46, v42, v48
	v_mov_b32_e32 v52, v41
	v_mov_b32_e32 v53, v40
	v_mul_f32_e32 v42, v135, v49
	v_pk_mul_f32 v[40:41], v[44:45], v[52:53]
	v_mul_f32_e32 v44, 0.15915494, v42
	v_rndne_f32_e32 v44, v44
	v_fmac_f32_e32 v42, 0xc0c90fdb, v44
	v_fmac_f32_e32 v42, 0x343bbd2e, v44
	v_mul_f32_e32 v42, 0.15915494, v42
	v_sin_f32_e32 v45, v42
	v_cos_f32_e32 v44, v42
	v_add_f32_e32 v40, v40, v41
	v_mov_b32_e32 v42, v47
	v_mul_f32_e32 v52, v40, v48
	v_pk_mul_f32 v[40:41], v[42:43], v[44:45]
	s_nop 0
	v_sub_f32_e32 v40, v40, v41
	v_mul_f32_e32 v47, v40, v48
	v_mov_b32_e32 v40, v45
	v_mov_b32_e32 v41, v44
	v_pk_mul_f32 v[40:41], v[42:43], v[40:41]
	v_add_co_u32_e32 v44, vcc, s71, v50
	v_add_f32_e32 v40, v40, v41
	v_mul_f32_e32 v43, v40, v48
	v_cvt_pk_bf16_f32 v40, v60, v59
	v_cvt_pk_bf16_f32 v41, v46, v47
	v_mul_f32_e32 v46, v128, v49
	v_mul_f32_e32 v47, 0.15915494, v46
	v_rndne_f32_e32 v47, v47
	v_fmac_f32_e32 v46, 0xc0c90fdb, v47
	v_fmac_f32_e32 v46, 0x343bbd2e, v47
	v_mul_f32_e32 v46, 0.15915494, v46
	v_sin_f32_e32 v47, v46
	v_cos_f32_e32 v46, v46
	v_addc_co_u32_e32 v45, vcc, 0, v51, vcc
	v_cvt_pk_bf16_f32 v42, v58, v54
	v_cvt_pk_bf16_f32 v43, v52, v43
	global_store_dwordx4 v[44:45], v[40:43], off
	s_and_b64 vcc, exec, s[4:5]
	s_nop 0
	v_mov_b32_e32 v40, v36
	v_mov_b32_e32 v41, v32
	v_pk_mul_f32 v[42:43], v[40:41], v[46:47]
	s_nop 0
	v_sub_f32_e32 v32, v42, v43
	v_mul_f32_e32 v44, v32, v48
	v_mul_f32_e32 v32, v129, v49
	v_mul_f32_e32 v36, 0.15915494, v32
	v_rndne_f32_e32 v36, v36
	v_fmac_f32_e32 v32, 0xc0c90fdb, v36
	v_fmac_f32_e32 v32, 0x343bbd2e, v36
	v_mov_b32_e32 v42, v47
	v_mov_b32_e32 v43, v46
	v_mul_f32_e32 v32, 0.15915494, v32
	v_pk_mul_f32 v[40:41], v[40:41], v[42:43]
	v_sin_f32_e32 v43, v32
	v_cos_f32_e32 v42, v32
	v_add_f32_e32 v32, v40, v41
	v_mul_f32_e32 v45, v32, v48
	v_mov_b32_e32 v32, v37
	v_pk_mul_f32 v[36:37], v[32:33], v[42:43]
	s_nop 0
	v_sub_f32_e32 v36, v36, v37
	v_mul_f32_e32 v46, v36, v48
	v_mov_b32_e32 v36, v43
	v_mov_b32_e32 v37, v42
	v_pk_mul_f32 v[32:33], v[32:33], v[36:37]
	v_mov_b32_e32 v37, v34
	v_add_f32_e32 v36, v32, v33
	v_mul_f32_e32 v32, v130, v49
	v_mul_f32_e32 v33, 0.15915494, v32
	v_rndne_f32_e32 v33, v33
	v_fmac_f32_e32 v32, 0xc0c90fdb, v33
	v_fmac_f32_e32 v32, 0x343bbd2e, v33
	v_mul_f32_e32 v32, 0.15915494, v32
	v_sin_f32_e32 v33, v32
	v_cos_f32_e32 v32, v32
	v_mul_f32_e32 v42, v36, v48
	v_mov_b32_e32 v36, v38
	v_pk_mul_f32 v[40:41], v[36:37], v[32:33]
	s_nop 0
	v_sub_f32_e32 v34, v40, v41
	v_mul_f32_e32 v38, v34, v48
	v_mov_b32_e32 v40, v33
	v_mov_b32_e32 v41, v32
	v_mul_f32_e32 v34, v131, v49
	v_pk_mul_f32 v[32:33], v[36:37], v[40:41]
	v_mul_f32_e32 v36, 0.15915494, v34
	v_rndne_f32_e32 v36, v36
	v_fmac_f32_e32 v34, 0xc0c90fdb, v36
	v_fmac_f32_e32 v34, 0x343bbd2e, v36
	v_mul_f32_e32 v34, 0.15915494, v34
	v_sin_f32_e32 v37, v34
	v_cos_f32_e32 v36, v34
	v_add_f32_e32 v32, v32, v33
	v_mov_b32_e32 v34, v39
	v_mul_f32_e32 v40, v32, v48
	v_pk_mul_f32 v[32:33], v[34:35], v[36:37]
	s_nop 0
	v_sub_f32_e32 v32, v32, v33
	v_mul_f32_e32 v39, v32, v48
	v_mov_b32_e32 v32, v37
	v_mov_b32_e32 v33, v36
	v_pk_mul_f32 v[32:33], v[34:35], v[32:33]
	s_nop 0
	v_add_f32_e32 v32, v32, v33
	v_mul_f32_e32 v35, v32, v48
	v_cvt_pk_bf16_f32 v32, v44, v46
	v_cvt_pk_bf16_f32 v33, v38, v39
	v_cvt_pk_bf16_f32 v34, v45, v42
	v_cvt_pk_bf16_f32 v35, v40, v35
	global_store_dwordx4 v[56:57], v[32:35], off offset:256
	s_nop 1
	v_mov_b32_e32 v33, v245
	s_cbranch_vccnz .LBB0_362
	v_cmp_gt_f32_e32 vcc, s68, v96
	s_mov_b64 s[0:1], 0
	s_nop 0
	v_cndmask_b32_e32 v34, 0, v173, vcc
	v_fmac_f32_e32 v34, v175, v167
	v_exp_f32_e32 v34, v34
	v_cndmask_b32_e32 v32, 0, v174, vcc
	v_ldexp_f32 v32, v34, v32

;     __device__ __forceinline__ void operator()(const f32x4 (&acc)[2][2][4][2], const Unit& u, int wr, int wc, int fr, int fq) const {
;     ...
;                 for (int m = 0; m < 4; ++m) {
;                     const int row = row0 + ai * HALF + m * 16; const float p = (float)pos[row];
;                     const float jj = (float)(wr * 64 + m * 16 + fr + 1);
;                     const float dec = isk ? 0.0625f * exp2f(-lg * jj) : exp2f(lg * jj);
; #pragma unroll
;                     for (int bj = 0; bj < 2; ++bj) { f32x4 o0, o1;
; #pragma unroll
;                         for (int e = 0; e < 4; ++e) { float s, c; sincos_rr(p * invf[bj][e], s, c);
;                             const float x1 = acc[ai][bj][m][0][e], x2 = acc[ai][bj][m][1][e];
;                             o0[e] = (x1 * c - x2 * s) * dec; o1[e] = (x2 * c + x1 * s) * dec; }
;                         st8(base + (size_t)row * 2048 + bj * HALF, o0, o1); }
.LBB0_364:
	v_cvt_f32_i32_e32 v33, v33
	v_mov_b32_e32 v36, v28
	v_lshlrev_b64 v[34:35], 12, v[158:159]
	v_lshl_add_u64 v[34:35], v[162:163], 0, v[34:35]
	v_mul_f32_e32 v28, v132, v33
	v_mul_f32_e32 v37, 0.15915494, v28
	v_rndne_f32_e32 v37, v37
	v_fmac_f32_e32 v28, 0xc0c90fdb, v37
	v_fmac_f32_e32 v28, 0x343bbd2e, v37
	v_mul_f32_e32 v28, 0.15915494, v28
	v_sin_f32_e32 v39, v28
	v_cos_f32_e32 v38, v28
	v_mov_b32_e32 v37, v24
	v_lshl_add_u64 v[40:41], v[34:35], 0, s[26:27]
	s_mov_b64 s[0:1], -1
	v_pk_mul_f32 v[42:43], v[36:37], v[38:39]
	s_nop 0
	v_sub_f32_e32 v24, v42, v43
	v_mul_f32_e32 v44, v24, v32
	v_mul_f32_e32 v24, v133, v33
	v_mul_f32_e32 v28, 0.15915494, v24
	v_rndne_f32_e32 v28, v28
	v_fmac_f32_e32 v24, 0xc0c90fdb, v28
	v_fmac_f32_e32 v24, 0x343bbd2e, v28
	v_mul_f32_e32 v24, 0.15915494, v24
	v_mov_b32_e32 v42, v39
	v_mov_b32_e32 v43, v38
	v_sin_f32_e32 v39, v24
	v_cos_f32_e32 v38, v24
	v_pk_mul_f32 v[36:37], v[36:37], v[42:43]
	s_nop 0
	v_add_f32_e32 v24, v36, v37
	v_mul_f32_e32 v42, v24, v32
	v_mov_b32_e32 v24, v29
	v_pk_mul_f32 v[28:29], v[24:25], v[38:39]
	s_nop 0
	v_sub_f32_e32 v28, v28, v29
	v_mul_f32_e32 v43, v28, v32
	v_mov_b32_e32 v28, v39
	v_mov_b32_e32 v29, v38
	v_pk_mul_f32 v[24:25], v[24:25], v[28:29]
	v_mov_b32_e32 v29, v26
	v_add_f32_e32 v28, v24, v25
	v_mul_f32_e32 v24, v134, v33
	v_mul_f32_e32 v25, 0.15915494, v24
	v_rndne_f32_e32 v25, v25
	v_fmac_f32_e32 v24, 0xc0c90fdb, v25
	v_fmac_f32_e32 v24, 0x343bbd2e, v25
	v_mul_f32_e32 v24, 0.15915494, v24
	v_sin_f32_e32 v25, v24
	v_cos_f32_e32 v24, v24
	v_mul_f32_e32 v38, v28, v32
	v_mov_b32_e32 v28, v30
	v_pk_mul_f32 v[36:37], v[28:29], v[24:25]
	s_nop 0
	v_sub_f32_e32 v26, v36, v37
	v_mul_f32_e32 v30, v26, v32
	v_mov_b32_e32 v36, v25
	v_mov_b32_e32 v37, v24
	v_mul_f32_e32 v26, v135, v33
	v_pk_mul_f32 v[24:25], v[28:29], v[36:37]
	v_mul_f32_e32 v28, 0.15915494, v26
	v_rndne_f32_e32 v28, v28
	v_fmac_f32_e32 v26, 0xc0c90fdb, v28
	v_fmac_f32_e32 v26, 0x343bbd2e, v28
	v_mul_f32_e32 v26, 0.15915494, v26
	v_sin_f32_e32 v29, v26
	v_cos_f32_e32 v28, v26
	v_add_f32_e32 v24, v24, v25
	v_mov_b32_e32 v26, v31
	v_mul_f32_e32 v36, v24, v32
	v_pk_mul_f32 v[24:25], v[26:27], v[28:29]
	s_nop 0
	v_sub_f32_e32 v24, v24, v25
	v_mul_f32_e32 v31, v24, v32
	v_mov_b32_e32 v24, v29
	v_mov_b32_e32 v25, v28
	v_pk_mul_f32 v[24:25], v[26:27], v[24:25]
	v_add_co_u32_e32 v28, vcc, s72, v34
	v_add_f32_e32 v24, v24, v25
	v_mul_f32_e32 v27, v24, v32
	v_cvt_pk_bf16_f32 v24, v44, v43
	v_cvt_pk_bf16_f32 v25, v30, v31
	v_mul_f32_e32 v30, v128, v33
	v_mul_f32_e32 v31, 0.15915494, v30
	v_rndne_f32_e32 v31, v31
	v_fmac_f32_e32 v30, 0xc0c90fdb, v31
	v_fmac_f32_e32 v30, 0x343bbd2e, v31
	v_mul_f32_e32 v30, 0.15915494, v30
	v_sin_f32_e32 v31, v30
	v_cos_f32_e32 v30, v30
	v_addc_co_u32_e32 v29, vcc, 0, v35, vcc
	v_cvt_pk_bf16_f32 v26, v42, v38
	v_cvt_pk_bf16_f32 v27, v36, v27
	global_store_dwordx4 v[28:29], v[24:27], off
	s_and_b64 vcc, exec, s[4:5]
	s_nop 0
	v_mov_b32_e32 v24, v20
	v_mov_b32_e32 v25, v16
	v_pk_mul_f32 v[26:27], v[24:25], v[30:31]
	s_nop 0
	v_sub_f32_e32 v16, v26, v27
	v_mul_f32_e32 v28, v16, v32
	v_mul_f32_e32 v16, v129, v33
	v_mul_f32_e32 v20, 0.15915494, v16
	v_rndne_f32_e32 v20, v20
	v_fmac_f32_e32 v16, 0xc0c90fdb, v20
	v_fmac_f32_e32 v16, 0x343bbd2e, v20
	v_mov_b32_e32 v26, v31
	v_mov_b32_e32 v27, v30
	v_mul_f32_e32 v16, 0.15915494, v16
	v_pk_mul_f32 v[24:25], v[24:25], v[26:27]
	v_sin_f32_e32 v27, v16
	v_cos_f32_e32 v26, v16
	v_add_f32_e32 v16, v24, v25
	v_mul_f32_e32 v29, v16, v32
	v_mov_b32_e32 v16, v21
	v_pk_mul_f32 v[20:21], v[16:17], v[26:27]
	s_nop 0
	v_sub_f32_e32 v20, v20, v21
	v_mul_f32_e32 v30, v20, v32
	v_mov_b32_e32 v20, v27
	v_mov_b32_e32 v21, v26
	v_pk_mul_f32 v[16:17], v[16:17], v[20:21]
	v_mov_b32_e32 v21, v18
	v_add_f32_e32 v20, v16, v17
	v_mul_f32_e32 v16, v130, v33
	v_mul_f32_e32 v17, 0.15915494, v16
	v_rndne_f32_e32 v17, v17
	v_fmac_f32_e32 v16, 0xc0c90fdb, v17
	v_fmac_f32_e32 v16, 0x343bbd2e, v17
	v_mul_f32_e32 v16, 0.15915494, v16
	v_sin_f32_e32 v17, v16
	v_cos_f32_e32 v16, v16
	v_mul_f32_e32 v26, v20, v32
	v_mov_b32_e32 v20, v22
	v_pk_mul_f32 v[24:25], v[20:21], v[16:17]
	s_nop 0
	v_sub_f32_e32 v18, v24, v25
	v_mul_f32_e32 v22, v18, v32
	v_mov_b32_e32 v24, v17
	v_mov_b32_e32 v25, v16
	v_mul_f32_e32 v18, v131, v33
	v_pk_mul_f32 v[16:17], v[20:21], v[24:25]
	v_mul_f32_e32 v20, 0.15915494, v18
	v_rndne_f32_e32 v20, v20
	v_fmac_f32_e32 v18, 0xc0c90fdb, v20
	v_fmac_f32_e32 v18, 0x343bbd2e, v20
	v_mul_f32_e32 v18, 0.15915494, v18
	v_sin_f32_e32 v21, v18
	v_cos_f32_e32 v20, v18
	v_add_f32_e32 v16, v16, v17
	v_mov_b32_e32 v18, v23
	v_mul_f32_e32 v24, v16, v32
	v_pk_mul_f32 v[16:17], v[18:19], v[20:21]
	s_nop 0
	v_sub_f32_e32 v16, v16, v17
	v_mul_f32_e32 v23, v16, v32
	v_mov_b32_e32 v16, v21
	v_mov_b32_e32 v17, v20
	v_pk_mul_f32 v[16:17], v[18:19], v[16:17]
	s_nop 0
	v_add_f32_e32 v16, v16, v17
	v_mul_f32_e32 v19, v16, v32
	v_cvt_pk_bf16_f32 v16, v28, v30
	v_cvt_pk_bf16_f32 v17, v22, v23
	v_cvt_pk_bf16_f32 v18, v29, v26
	v_cvt_pk_bf16_f32 v19, v24, v19
	global_store_dwordx4 v[40:41], v[16:19], off offset:256
	s_nop 1
	v_mov_b32_e32 v17, v246
	s_cbranch_vccnz .LBB0_366
	v_cmp_gt_f32_e32 vcc, s68, v80
	s_mov_b64 s[0:1], 0
	s_nop 0
	v_cndmask_b32_e32 v18, 0, v173, vcc
	v_fmac_f32_e32 v18, v175, v169
	v_exp_f32_e32 v18, v18
	v_cndmask_b32_e32 v16, 0, v174, vcc
	v_ldexp_f32 v16, v18, v16

;     __device__ __forceinline__ void operator()(const f32x4 (&acc)[2][2][4][2], const Unit& u, int wr, int wc, int fr, int fq) const {
;     ...
;                 for (int m = 0; m < 4; ++m) {
;                     const int row = row0 + ai * HALF + m * 16; const float p = (float)pos[row];
;                     const float jj = (float)(wr * 64 + m * 16 + fr + 1);
;                     const float dec = isk ? 0.0625f * exp2f(-lg * jj) : exp2f(lg * jj);
; #pragma unroll
;                     for (int bj = 0; bj < 2; ++bj) { f32x4 o0, o1;
; #pragma unroll
;                         for (int e = 0; e < 4; ++e) { float s, c; sincos_rr(p * invf[bj][e], s, c);
;                             const float x1 = acc[ai][bj][m][0][e], x2 = acc[ai][bj][m][1][e];
;                             o0[e] = (x1 * c - x2 * s) * dec; o1[e] = (x2 * c + x1 * s) * dec; }
;                         st8(base + (size_t)row * 2048 + bj * HALF, o0, o1); }
.LBB0_368:
	v_cvt_f32_i32_e32 v17, v17
	v_mov_b32_e32 v20, v12
	v_lshlrev_b64 v[18:19], 12, v[158:159]
	v_lshl_add_u64 v[18:19], v[162:163], 0, v[18:19]
	v_mul_f32_e32 v12, v132, v17
	v_mul_f32_e32 v21, 0.15915494, v12
	v_rndne_f32_e32 v21, v21
	v_fmac_f32_e32 v12, 0xc0c90fdb, v21
	v_fmac_f32_e32 v12, 0x343bbd2e, v21
	v_mul_f32_e32 v12, 0.15915494, v12
	v_sin_f32_e32 v23, v12
	v_cos_f32_e32 v22, v12
	v_mov_b32_e32 v21, v8
	v_lshl_add_u64 v[24:25], v[18:19], 0, s[28:29]
	v_pk_mul_f32 v[26:27], v[20:21], v[22:23]
	s_nop 0
	v_sub_f32_e32 v8, v26, v27
	v_mul_f32_e32 v28, v8, v16
	v_mul_f32_e32 v8, v133, v17
	v_mul_f32_e32 v12, 0.15915494, v8
	v_rndne_f32_e32 v12, v12
	v_fmac_f32_e32 v8, 0xc0c90fdb, v12
	v_fmac_f32_e32 v8, 0x343bbd2e, v12
	v_mul_f32_e32 v8, 0.15915494, v8
	v_mov_b32_e32 v26, v23
	v_mov_b32_e32 v27, v22
	v_sin_f32_e32 v23, v8
	v_cos_f32_e32 v22, v8
	v_pk_mul_f32 v[20:21], v[20:21], v[26:27]
	s_nop 0
	v_add_f32_e32 v8, v20, v21
	v_mul_f32_e32 v26, v8, v16
	v_mov_b32_e32 v8, v13
	v_pk_mul_f32 v[12:13], v[8:9], v[22:23]
	s_nop 0
	v_sub_f32_e32 v12, v12, v13
	v_mul_f32_e32 v27, v12, v16
	v_mov_b32_e32 v12, v23
	v_mov_b32_e32 v13, v22
	v_pk_mul_f32 v[8:9], v[8:9], v[12:13]
	v_mov_b32_e32 v13, v10
	v_add_f32_e32 v12, v8, v9
	v_mul_f32_e32 v8, v134, v17
	v_mul_f32_e32 v9, 0.15915494, v8
	v_rndne_f32_e32 v9, v9
	v_fmac_f32_e32 v8, 0xc0c90fdb, v9
	v_fmac_f32_e32 v8, 0x343bbd2e, v9
	v_mul_f32_e32 v8, 0.15915494, v8
	v_sin_f32_e32 v9, v8
	v_cos_f32_e32 v8, v8
	v_mul_f32_e32 v22, v12, v16
	v_mov_b32_e32 v12, v14
	v_pk_mul_f32 v[20:21], v[12:13], v[8:9]
	s_nop 0
	v_sub_f32_e32 v10, v20, v21
	v_mul_f32_e32 v14, v10, v16
	v_mov_b32_e32 v20, v9
	v_mov_b32_e32 v21, v8
	v_mul_f32_e32 v10, v135, v17
	v_pk_mul_f32 v[8:9], v[12:13], v[20:21]
	v_mul_f32_e32 v12, 0.15915494, v10
	v_rndne_f32_e32 v12, v12
	v_fmac_f32_e32 v10, 0xc0c90fdb, v12
	v_fmac_f32_e32 v10, 0x343bbd2e, v12
	v_mul_f32_e32 v10, 0.15915494, v10
	v_sin_f32_e32 v13, v10
	v_cos_f32_e32 v12, v10
	v_add_f32_e32 v8, v8, v9
	v_mov_b32_e32 v10, v15
	v_mul_f32_e32 v20, v8, v16
	v_pk_mul_f32 v[8:9], v[10:11], v[12:13]
	s_nop 0
	v_sub_f32_e32 v8, v8, v9
	v_mul_f32_e32 v15, v8, v16
	v_mov_b32_e32 v8, v13
	v_mov_b32_e32 v9, v12
	v_pk_mul_f32 v[8:9], v[10:11], v[8:9]
	v_add_co_u32_e32 v12, vcc, s73, v18
	v_add_f32_e32 v8, v8, v9
	v_mul_f32_e32 v11, v8, v16
	v_cvt_pk_bf16_f32 v8, v28, v27
	v_cvt_pk_bf16_f32 v9, v14, v15
	v_mul_f32_e32 v14, v128, v17
	v_mul_f32_e32 v15, 0.15915494, v14
	v_rndne_f32_e32 v15, v15
	v_fmac_f32_e32 v14, 0xc0c90fdb, v15
	v_fmac_f32_e32 v14, 0x343bbd2e, v15
	v_mul_f32_e32 v14, 0.15915494, v14
	v_sin_f32_e32 v15, v14
	v_cos_f32_e32 v14, v14
	v_addc_co_u32_e32 v13, vcc, 0, v19, vcc
	v_cvt_pk_bf16_f32 v10, v26, v22
	v_cvt_pk_bf16_f32 v11, v20, v11
	global_store_dwordx4 v[12:13], v[8:11], off
	s_nop 1
	v_mov_b32_e32 v8, v4
	v_mov_b32_e32 v9, v0
	v_pk_mul_f32 v[10:11], v[8:9], v[14:15]
	s_nop 0
	v_sub_f32_e32 v0, v10, v11
	v_mul_f32_e32 v12, v0, v16
	v_mul_f32_e32 v0, v129, v17
	v_mul_f32_e32 v4, 0.15915494, v0
	v_rndne_f32_e32 v4, v4
	v_fmac_f32_e32 v0, 0xc0c90fdb, v4
	v_fmac_f32_e32 v0, 0x343bbd2e, v4
	v_mov_b32_e32 v10, v15
	v_mov_b32_e32 v11, v14
	v_mul_f32_e32 v0, 0.15915494, v0
	v_pk_mul_f32 v[8:9], v[8:9], v[10:11]
	v_sin_f32_e32 v11, v0
	v_cos_f32_e32 v10, v0
	v_add_f32_e32 v0, v8, v9
	v_mul_f32_e32 v13, v0, v16
	v_mov_b32_e32 v0, v5
	v_pk_mul_f32 v[4:5], v[0:1], v[10:11]
	s_nop 0
	v_sub_f32_e32 v4, v4, v5
	v_mul_f32_e32 v14, v4, v16
	v_mov_b32_e32 v4, v11
	v_mov_b32_e32 v5, v10
	v_pk_mul_f32 v[0:1], v[0:1], v[4:5]
	v_mov_b32_e32 v5, v2
	v_add_f32_e32 v4, v0, v1
	v_mul_f32_e32 v0, v130, v17
	v_mul_f32_e32 v1, 0.15915494, v0
	v_rndne_f32_e32 v1, v1
	v_fmac_f32_e32 v0, 0xc0c90fdb, v1
	v_fmac_f32_e32 v0, 0x343bbd2e, v1
	v_mul_f32_e32 v0, 0.15915494, v0
	v_sin_f32_e32 v1, v0
	v_cos_f32_e32 v0, v0
	v_mul_f32_e32 v10, v4, v16
	v_mov_b32_e32 v4, v6
	v_pk_mul_f32 v[8:9], v[4:5], v[0:1]
	s_nop 0
	v_sub_f32_e32 v2, v8, v9
	v_mul_f32_e32 v6, v2, v16
	v_mov_b32_e32 v8, v1
	v_mov_b32_e32 v9, v0
	v_mul_f32_e32 v2, v131, v17
	v_pk_mul_f32 v[0:1], v[4:5], v[8:9]
	v_mul_f32_e32 v4, 0.15915494, v2
	v_rndne_f32_e32 v4, v4
	v_fmac_f32_e32 v2, 0xc0c90fdb, v4
	v_fmac_f32_e32 v2, 0x343bbd2e, v4
	v_mul_f32_e32 v2, 0.15915494, v2
	v_sin_f32_e32 v5, v2
	v_cos_f32_e32 v4, v2
	v_add_f32_e32 v0, v0, v1
	v_mov_b32_e32 v2, v7
	v_mul_f32_e32 v8, v0, v16
	v_pk_mul_f32 v[0:1], v[2:3], v[4:5]
	s_nop 0
	v_sub_f32_e32 v0, v0, v1
	v_mul_f32_e32 v7, v0, v16
	v_mov_b32_e32 v0, v5
	v_mov_b32_e32 v1, v4
	v_pk_mul_f32 v[0:1], v[2:3], v[0:1]
	s_nop 0
	v_add_f32_e32 v0, v0, v1
	v_mul_f32_e32 v3, v0, v16
	v_cvt_pk_bf16_f32 v0, v12, v14
	v_cvt_pk_bf16_f32 v1, v6, v7
	v_cvt_pk_bf16_f32 v2, v13, v10
	v_cvt_pk_bf16_f32 v3, v8, v3
	global_store_dwordx4 v[24:25], v[0:3], off offset:256
	s_andn2_b64 vcc, exec, s[2:3]
	s_mov_b64 s[0:1], -1
	s_cbranch_vccnz .LBB0_293
